# hyena: A fragments fetched as aligned dwords + v_alignbit instead of 8 ds_read_u16
# speedup vs baseline: 1.0326x; 1.0010x over previous
.Lhy_gw_short:
	s_waitcnt vmcnt(0)
	ds_write_b128 v6, v[72:75]
	ds_write_b128 v6, v[76:79] offset:1280
	ds_write_b128 v6, v[80:83] offset:2560
	ds_write_b128 v6, v[84:87] offset:3840
	s_or_b64 exec, exec, s[14:15]
	v_cmp_gt_i32_e32 vcc, 8, v34
	s_and_saveexec_b64 s[14:15], vcc
	v_lshl_add_u32 v0, v34, 2, 0
	v_add_u32_e32 v0, 0x1a000, v0
	ds_write_b32 v0, v1
	s_or_b64 exec, exec, s[14:15]
	s_lshr_b32 s6, s7, 5
	s_and_b64 s[4:5], s[40:41], exec
	s_cselect_b32 s10, 3, 5
	s_add_i32 s11, s6, -1
	v_and_b32_e32 v2, 31, v34
	s_and_b64 s[4:5], s[40:41], exec
	s_cselect_b32 s4, 8, 10
	v_lshrrev_b32_e32 v0, s10, v2
	v_lshlrev_b32_e32 v38, s4, v0
	v_or_b32_e32 v0, 32, v2
	v_lshl_add_u32 v3, s7, 2, v5
	v_lshlrev_b32_e32 v2, 1, v2
	v_bitop3_b32 v37, v34, s11, 31 bitop3:0x80
	v_lshrrev_b32_e32 v0, s10, v0
	v_sub_u32_e32 v2, v3, v2
	v_readlane_b32 s5, v253, 18
	v_lshlrev_b32_e32 v0, s4, v0
	v_lshlrev_b32_e32 v4, 1, v0
	v_add_u32_e32 v40, s5, v2
	v_add_u32_e32 v2, s6, v37
	v_lshl_add_u32 v3, v2, 6, v5
	v_lshrrev_b32_e32 v36, 5, v8
	s_lshr_b32 s4, s7, 4
	v_add3_u32 v41, v3, v4, 0
	v_lshlrev_b32_e32 v4, 1, v38
	v_mov_b32_e32 v18, 0
	v_lshlrev_b32_e32 v39, 4, v36
	s_add_i32 s7, s4, -1
	v_add3_u32 v42, v3, v4, 0
	v_lshrrev_b32_e32 v44, 5, v0
	v_lshrrev_b32_e32 v45, 5, v38
	v_add_u32_e32 v44, v44, v2
	v_add_u32_e32 v45, v45, v2
	v_lshlrev_b32_e32 v44, 4, v44
	v_lshlrev_b32_e32 v45, 4, v45
	v_lshl_add_u32 v44, v35, 10, v44
	v_lshl_add_u32 v45, v35, 10, v45
	v_add_u32_e32 v41, v41, v44
	v_add_u32_e32 v42, v42, v45
	v_add_u32_e32 v43, -1, v2
	v_mov_b32_e32 v19, v18
	v_mov_b32_e32 v20, v18
	v_mov_b32_e32 v21, v18
	v_mov_b32_e32 v22, v18
	v_mov_b32_e32 v23, v18
	v_mov_b32_e32 v24, v18
	v_mov_b32_e32 v25, v18
	v_mov_b32_e32 v26, v18
	v_mov_b32_e32 v27, v18
	v_mov_b32_e32 v28, v18
	v_mov_b32_e32 v29, v18
	v_mov_b32_e32 v30, v18
	v_mov_b32_e32 v31, v18
	v_mov_b32_e32 v32, v18
	v_mov_b32_e32 v33, v18
	v_mov_b32_e32 v2, v18
	v_mov_b32_e32 v3, v18
	v_mov_b32_e32 v4, v18
	v_mov_b32_e32 v5, v18
	v_mov_b32_e32 v6, v18
	v_mov_b32_e32 v7, v18
	v_mov_b32_e32 v8, v18
	v_mov_b32_e32 v9, v18
	v_mov_b32_e32 v10, v18
	v_mov_b32_e32 v11, v18
	v_mov_b32_e32 v12, v18
	v_mov_b32_e32 v13, v18
	v_mov_b32_e32 v14, v18
	v_mov_b32_e32 v15, v18
	v_mov_b32_e32 v16, v18
	v_mov_b32_e32 v17, v18
	s_waitcnt lgkmcnt(0)
	s_barrier
	v_add_u32_e32 v124, v40, v39
	v_and_b32_e32 v124, 2, v124
	v_lshlrev_b32_e32 v124, 3, v124
	s_add_i32 s4, 0, 0x1a000
	v_mov_b32_e32 v54, s4
	v_add_u32_e32 v52, v40, v39
	v_and_b32_e32 v52, -4, v52
	s_nop 0
	ds_read2_b32 v[104:105], v52 offset1:1
	ds_read2_b32 v[106:107], v52 offset0:2 offset1:3
	ds_read_b32 v108, v52 offset:16
	v_cmp_lt_i32_e32 vcc, -1, v43
	v_cmp_gt_i32_e64 s[40:41], s6, v43
	v_add_u32_e32 v53, v42, v39
	v_add_u32_e32 v55, v41, v39
	s_and_b64 vcc, vcc, s[40:41]
	v_add_u32_e32 v120, 0xffb0, v53
	v_add_u32_e32 v121, 0xffb0, v55
	v_add_u32_e32 v122, 0xffd0, v53
	v_add_u32_e32 v123, 0xffd0, v55
	v_cndmask_b32_e32 v120, v54, v120, vcc
	v_cndmask_b32_e32 v121, v54, v121, vcc
	v_cndmask_b32_e32 v122, v54, v122, vcc
	v_cndmask_b32_e32 v123, v54, v123, vcc
	ds_read_b128 v[48:51], v120
	ds_read_b128 v[92:95], v121
	ds_read_b128 v[96:99], v122
	ds_read_b128 v[100:103], v123
	ds_read2_b32 v[112:113], v52 offset0:8 offset1:9
	ds_read2_b32 v[114:115], v52 offset0:10 offset1:11
	ds_read_b32 v116, v52 offset:48
	v_subrev_u32_e32 v40, 64, v40
	v_subrev_u32_e32 v41, 0x50, v41
	v_subrev_u32_e32 v42, 0x50, v42
	v_add_u32_e32 v43, -1, v43
	s_waitcnt lgkmcnt(0)
	v_alignbit_b32 v44, v105, v104, v124
	v_alignbit_b32 v45, v106, v105, v124
	v_alignbit_b32 v46, v107, v106, v124
	v_alignbit_b32 v47, v108, v107, v124
	v_alignbit_b32 v88, v113, v112, v124
	v_alignbit_b32 v89, v114, v113, v124
	v_alignbit_b32 v90, v115, v114, v124
	v_alignbit_b32 v91, v116, v115, v124
.LBB0_532:
	v_mfma_f32_32x32x16_bf16 v[18:33], v[44:47], v[48:51], v[18:33]
	v_mfma_f32_32x32x16_bf16 v[2:17], v[44:47], v[92:95], v[2:17]
	v_mfma_f32_32x32x16_bf16 v[18:33], v[88:91], v[96:99], v[18:33]
	v_mfma_f32_32x32x16_bf16 v[2:17], v[88:91], v[100:103], v[2:17]
	s_add_i32 s7, s7, -1
	v_add_u32_e32 v52, v40, v39
	v_and_b32_e32 v52, -4, v52
	s_nop 0
	ds_read2_b32 v[104:105], v52 offset1:1
	ds_read2_b32 v[106:107], v52 offset0:2 offset1:3
	ds_read_b32 v108, v52 offset:16
	v_cmp_lt_i32_e32 vcc, -1, v43
	v_cmp_gt_i32_e64 s[40:41], s6, v43
	v_add_u32_e32 v53, v42, v39
	v_add_u32_e32 v55, v41, v39
	s_and_b64 vcc, vcc, s[40:41]
	v_add_u32_e32 v120, 0xffb0, v53
	v_add_u32_e32 v121, 0xffb0, v55
	v_add_u32_e32 v122, 0xffd0, v53
	v_add_u32_e32 v123, 0xffd0, v55
	v_cndmask_b32_e32 v120, v54, v120, vcc
	v_cndmask_b32_e32 v121, v54, v121, vcc
	v_cndmask_b32_e32 v122, v54, v122, vcc
	v_cndmask_b32_e32 v123, v54, v123, vcc
	ds_read_b128 v[48:51], v120
	ds_read_b128 v[92:95], v121
	ds_read_b128 v[96:99], v122
	ds_read_b128 v[100:103], v123
	ds_read2_b32 v[112:113], v52 offset0:8 offset1:9
	ds_read2_b32 v[114:115], v52 offset0:10 offset1:11
	ds_read_b32 v116, v52 offset:48
	v_subrev_u32_e32 v40, 64, v40
	v_subrev_u32_e32 v41, 0x50, v41
	v_subrev_u32_e32 v42, 0x50, v42
	v_add_u32_e32 v43, -1, v43
	s_waitcnt lgkmcnt(0)
	v_alignbit_b32 v44, v105, v104, v124
	v_alignbit_b32 v45, v106, v105, v124
	v_alignbit_b32 v46, v107, v106, v124
	v_alignbit_b32 v47, v108, v107, v124
	v_alignbit_b32 v88, v113, v112, v124
	v_alignbit_b32 v89, v114, v113, v124
	v_alignbit_b32 v90, v115, v114, v124
	v_alignbit_b32 v91, v116, v115, v124
	s_cmp_lg_u32 s7, 0
	s_cbranch_scc1 .LBB0_532
	s_barrier
	v_lshlrev_b32_e32 v37, 5, v37
	v_lshlrev_b32_e32 v36, 2, v36
	v_add_u32_e32 v38, v38, v37
	v_lshl_add_u32 v35, v35, 1, 0
	v_or_b32_e32 v38, v38, v36
	v_bfe_u32 v39, v18, 16, 1
	v_add3_u32 v18, v18, v39, s27
	v_lshrrev_b32_e32 v56, 5, v38
	v_lshl_add_u32 v38, v38, 4, v35
	v_lshl_add_u32 v38, v56, 4, v38
	ds_write_b16_d16_hi v38, v18
	v_bfe_u32 v18, v19, 16, 1
	v_add3_u32 v18, v19, v18, s27
	ds_write_b16_d16_hi v38, v18 offset:16
	v_bfe_u32 v18, v20, 16, 1
	v_add3_u32 v18, v20, v18, s27
	ds_write_b16_d16_hi v38, v18 offset:32
	v_bfe_u32 v18, v21, 16, 1
	v_add3_u32 v18, v21, v18, s27
	ds_write_b16_d16_hi v38, v18 offset:48
	v_bfe_u32 v18, v22, 16, 1
	v_add3_u32 v18, v22, v18, s27
	ds_write_b16_d16_hi v38, v18 offset:128
	v_bfe_u32 v18, v23, 16, 1
	v_add3_u32 v18, v23, v18, s27
	ds_write_b16_d16_hi v38, v18 offset:144
	v_bfe_u32 v18, v24, 16, 1
	v_add3_u32 v18, v24, v18, s27
	ds_write_b16_d16_hi v38, v18 offset:160
	v_bfe_u32 v18, v25, 16, 1
	v_add3_u32 v18, v25, v18, s27
	ds_write_b16_d16_hi v38, v18 offset:176
	v_bfe_u32 v18, v26, 16, 1
	v_add3_u32 v18, v26, v18, s27
	ds_write_b16_d16_hi v38, v18 offset:256
	v_bfe_u32 v18, v27, 16, 1
	v_add3_u32 v18, v27, v18, s27
	ds_write_b16_d16_hi v38, v18 offset:272
	v_bfe_u32 v18, v28, 16, 1
	v_add3_u32 v18, v28, v18, s27
	ds_write_b16_d16_hi v38, v18 offset:288
	v_bfe_u32 v18, v29, 16, 1
	v_add3_u32 v18, v29, v18, s27
	ds_write_b16_d16_hi v38, v18 offset:304
	v_bfe_u32 v18, v30, 16, 1
	v_add3_u32 v18, v30, v18, s27
	ds_write_b16_d16_hi v38, v18 offset:384
	v_bfe_u32 v18, v31, 16, 1
	v_add3_u32 v18, v31, v18, s27
	ds_write_b16_d16_hi v38, v18 offset:400
	v_bfe_u32 v18, v32, 16, 1
	v_add3_u32 v18, v32, v18, s27
	ds_write_b16_d16_hi v38, v18 offset:416
	v_bfe_u32 v18, v33, 16, 1
	v_add3_u32 v18, v33, v18, s27
	v_add_u32_e32 v0, v0, v37
	ds_write_b16_d16_hi v38, v18 offset:432
	v_or_b32_e32 v0, v0, v36
	v_bfe_u32 v18, v2, 16, 1
	v_add3_u32 v2, v2, v18, s27
	v_lshrrev_b32_e32 v57, 5, v0
	v_lshl_add_u32 v0, v0, 4, v35
	v_lshl_add_u32 v0, v57, 4, v0
	ds_write_b16_d16_hi v0, v2
	v_bfe_u32 v2, v3, 16, 1
	v_add3_u32 v2, v3, v2, s27
	ds_write_b16_d16_hi v0, v2 offset:16
	v_bfe_u32 v2, v4, 16, 1
	v_add3_u32 v2, v4, v2, s27
	ds_write_b16_d16_hi v0, v2 offset:32
	v_bfe_u32 v2, v5, 16, 1
	v_add3_u32 v2, v5, v2, s27
	ds_write_b16_d16_hi v0, v2 offset:48
	v_bfe_u32 v2, v6, 16, 1
	v_add3_u32 v2, v6, v2, s27
	ds_write_b16_d16_hi v0, v2 offset:128
	v_bfe_u32 v2, v7, 16, 1
	v_add3_u32 v2, v7, v2, s27
	ds_write_b16_d16_hi v0, v2 offset:144
	v_bfe_u32 v2, v8, 16, 1
	v_add3_u32 v2, v8, v2, s27
	ds_write_b16_d16_hi v0, v2 offset:160
	v_bfe_u32 v2, v9, 16, 1
	v_add3_u32 v2, v9, v2, s27
	ds_write_b16_d16_hi v0, v2 offset:176
	v_bfe_u32 v2, v10, 16, 1
	v_add3_u32 v2, v10, v2, s27
	ds_write_b16_d16_hi v0, v2 offset:256
	v_bfe_u32 v2, v11, 16, 1
	v_add3_u32 v2, v11, v2, s27
	ds_write_b16_d16_hi v0, v2 offset:272
	v_bfe_u32 v2, v12, 16, 1
	v_add3_u32 v2, v12, v2, s27
	ds_write_b16_d16_hi v0, v2 offset:288
	v_bfe_u32 v2, v13, 16, 1
	v_add3_u32 v2, v13, v2, s27
	ds_write_b16_d16_hi v0, v2 offset:304
	v_bfe_u32 v2, v14, 16, 1
	v_add3_u32 v2, v14, v2, s27
	ds_write_b16_d16_hi v0, v2 offset:384
	v_bfe_u32 v2, v15, 16, 1
	v_add3_u32 v2, v15, v2, s27
	ds_write_b16_d16_hi v0, v2 offset:400
	v_bfe_u32 v2, v16, 16, 1
	v_add3_u32 v2, v16, v2, s27
	ds_write_b16_d16_hi v0, v2 offset:416
	v_bfe_u32 v2, v17, 16, 1
	s_movk_i32 s4, 0x800
	v_add3_u32 v2, v17, v2, s27
	v_cmp_gt_i32_e32 vcc, s4, v34
	ds_write_b16_d16_hi v0, v2 offset:432
	s_waitcnt lgkmcnt(0)
	s_barrier
	s_and_saveexec_b64 s[40:41], vcc
	s_mov_b64 s[10:11], 0x100000
	s_cbranch_execz .LBB0_497
	s_add_i32 s4, s38, s3
	s_ashr_i32 s5, s4, 31
	s_lshl_b64 s[4:5], s[4:5], 2
	s_add_u32 s4, s42, s4
	s_addc_u32 s5, s43, s5
	global_load_dwordx4 v[2:5], v1, s[4:5] offset:16
	global_load_dwordx4 v[6:9], v1, s[4:5]
	s_ashr_i32 s39, s38, 31
	v_add_u32_e32 v12, s44, v34
	s_lshl_b64 s[4:5], s[38:39], 1
	v_readlane_b32 s6, v253, 50
	v_ashrrev_i32_e32 v13, 31, v12
	v_readlane_b32 s7, v253, 51
	s_add_u32 s6, s6, s4
	v_lshlrev_b64 v[10:11], 11, v[12:13]
	s_addc_u32 s7, s7, s5
	v_lshl_add_u64 v[10:11], s[6:7], 0, v[10:11]
	v_readlane_b32 s6, v254, 49
	v_readlane_b32 s7, v254, 50
	s_add_u32 s4, s6, s4
	v_lshlrev_b64 v[12:13], 10, v[12:13]
	s_addc_u32 s5, s7, s5
	v_add_u32_e32 v0, 0xfffffe00, v34
	v_lshl_add_u32 v14, v34, 4, 0
	v_lshrrev_b32_e32 v15, 5, v34
	v_lshl_add_u32 v14, v15, 4, v14
	v_lshl_add_u64 v[12:13], s[4:5], 0, v[12:13]
	s_mov_b64 s[38:39], 0
	s_mov_b64 s[4:5], 0x80000
	global_load_dwordx4 v[56:59], v[12:13], off
	v_add_co_u32_e32 v24, vcc, 0x600000, v12
	s_nop 1
	v_addc_co_u32_e32 v25, vcc, 0, v13, vcc
	global_load_dwordx4 v[72:75], v[24:25], off
	ds_read_b128 v[88:91], v14
	v_lshl_add_u64 v[12:13], v[12:13], 0, s[4:5]
	global_load_dwordx4 v[60:63], v[12:13], off
	v_add_co_u32_e32 v24, vcc, 0x600000, v12
	s_nop 1
	v_addc_co_u32_e32 v25, vcc, 0, v13, vcc
	global_load_dwordx4 v[76:79], v[24:25], off
	ds_read_b128 v[92:95], v14 offset:8448
	v_lshl_add_u64 v[12:13], v[12:13], 0, s[4:5]
	global_load_dwordx4 v[64:67], v[12:13], off
	v_add_co_u32_e32 v24, vcc, 0x600000, v12
	s_nop 1
	v_addc_co_u32_e32 v25, vcc, 0, v13, vcc
	global_load_dwordx4 v[80:83], v[24:25], off
	ds_read_b128 v[96:99], v14 offset:16896
	v_lshl_add_u64 v[12:13], v[12:13], 0, s[4:5]
	global_load_dwordx4 v[68:71], v[12:13], off
	v_add_co_u32_e32 v24, vcc, 0x600000, v12
	s_nop 1
	v_addc_co_u32_e32 v25, vcc, 0, v13, vcc
	global_load_dwordx4 v[84:87], v[24:25], off
	ds_read_b128 v[100:103], v14 offset:25344
	v_lshl_add_u64 v[12:13], v[12:13], 0, s[4:5]
	s_waitcnt vmcnt(6) lgkmcnt(3)
	v_mov_b32_e32 v16, v88
	v_mov_b32_e32 v17, v89
	v_mov_b32_e32 v18, v90
	v_mov_b32_e32 v19, v91
	v_mov_b32_e32 v20, v56
	v_mov_b32_e32 v21, v57
	v_mov_b32_e32 v22, v58
	v_mov_b32_e32 v23, v59
	v_mov_b32_e32 v24, v72
	v_mov_b32_e32 v25, v73
	v_mov_b32_e32 v26, v74
	v_mov_b32_e32 v27, v75
	v_and_b32_e32 v31, 0xffff0000, v16
	v_lshlrev_b32_e32 v30, 16, v16
	v_and_b32_e32 v29, 0xffff0000, v20
	v_lshlrev_b32_e32 v28, 16, v20
	v_lshlrev_b32_e32 v20, 16, v17
	v_and_b32_e32 v33, 0xffff0000, v24
	v_lshlrev_b32_e32 v32, 16, v24
	v_pk_fma_f32 v[30:31], v[6:7], v[32:33], v[30:31]
	v_lshlrev_b32_e32 v16, 16, v25
	v_pk_mul_f32 v[28:29], v[30:31], v[28:29]
	v_and_b32_e32 v31, 0xffff0000, v21
	v_lshlrev_b32_e32 v30, 16, v21
	v_and_b32_e32 v21, 0xffff0000, v17
	v_and_b32_e32 v17, 0xffff0000, v25
	v_pk_fma_f32 v[16:17], v[8:9], v[16:17], v[20:21]
	v_and_b32_e32 v25, 0xffff0000, v18
	v_pk_mul_f32 v[20:21], v[16:17], v[30:31]
	v_lshlrev_b32_e32 v24, 16, v18
	v_and_b32_e32 v31, 0xffff0000, v26
	v_lshlrev_b32_e32 v30, 16, v26
	v_and_b32_e32 v17, 0xffff0000, v22
	v_lshlrev_b32_e32 v16, 16, v22
	v_pk_fma_f32 v[24:25], v[2:3], v[30:31], v[24:25]
	v_lshlrev_b32_e32 v22, 16, v19
	v_pk_mul_f32 v[24:25], v[24:25], v[16:17]
	v_and_b32_e32 v17, 0xffff0000, v23
	v_lshlrev_b32_e32 v16, 16, v23
	v_and_b32_e32 v23, 0xffff0000, v19
	v_and_b32_e32 v19, 0xffff0000, v27
	v_lshlrev_b32_e32 v18, 16, v27
	v_pk_fma_f32 v[18:19], v[4:5], v[18:19], v[22:23]
	s_nop 0
	v_pk_mul_f32 v[22:23], v[18:19], v[16:17]
	v_cvt_pk_bf16_f32 v16, v28, v29
	v_cvt_pk_bf16_f32 v17, v20, v21
	v_cvt_pk_bf16_f32 v18, v24, v25
	v_cvt_pk_bf16_f32 v19, v22, v23
	global_store_dwordx4 v[10:11], v[16:19], off
	v_lshl_add_u64 v[10:11], v[10:11], 0, s[10:11]
	s_nop 1
	s_waitcnt vmcnt(5) lgkmcnt(2)
	v_mov_b32_e32 v16, v92
	v_mov_b32_e32 v17, v93
	v_mov_b32_e32 v18, v94
	v_mov_b32_e32 v19, v95
	v_mov_b32_e32 v20, v60
	v_mov_b32_e32 v21, v61
	v_mov_b32_e32 v22, v62
	v_mov_b32_e32 v23, v63
	v_mov_b32_e32 v24, v76
	v_mov_b32_e32 v25, v77
	v_mov_b32_e32 v26, v78
	v_mov_b32_e32 v27, v79
	v_and_b32_e32 v31, 0xffff0000, v16
	v_lshlrev_b32_e32 v30, 16, v16
	v_and_b32_e32 v29, 0xffff0000, v20
	v_lshlrev_b32_e32 v28, 16, v20
	v_lshlrev_b32_e32 v20, 16, v17
	v_and_b32_e32 v33, 0xffff0000, v24
	v_lshlrev_b32_e32 v32, 16, v24
	v_pk_fma_f32 v[30:31], v[6:7], v[32:33], v[30:31]
	v_lshlrev_b32_e32 v16, 16, v25
	v_pk_mul_f32 v[28:29], v[30:31], v[28:29]
	v_and_b32_e32 v31, 0xffff0000, v21
	v_lshlrev_b32_e32 v30, 16, v21
	v_and_b32_e32 v21, 0xffff0000, v17
	v_and_b32_e32 v17, 0xffff0000, v25
	v_pk_fma_f32 v[16:17], v[8:9], v[16:17], v[20:21]
	v_and_b32_e32 v25, 0xffff0000, v18
	v_pk_mul_f32 v[20:21], v[16:17], v[30:31]
	v_lshlrev_b32_e32 v24, 16, v18
	v_and_b32_e32 v31, 0xffff0000, v26
	v_lshlrev_b32_e32 v30, 16, v26
	v_and_b32_e32 v17, 0xffff0000, v22
	v_lshlrev_b32_e32 v16, 16, v22
	v_pk_fma_f32 v[24:25], v[2:3], v[30:31], v[24:25]
	v_lshlrev_b32_e32 v22, 16, v19
	v_pk_mul_f32 v[24:25], v[24:25], v[16:17]
	v_and_b32_e32 v17, 0xffff0000, v23
	v_lshlrev_b32_e32 v16, 16, v23
	v_and_b32_e32 v23, 0xffff0000, v19
	v_and_b32_e32 v19, 0xffff0000, v27
	v_lshlrev_b32_e32 v18, 16, v27
	v_pk_fma_f32 v[18:19], v[4:5], v[18:19], v[22:23]
	s_nop 0
	v_pk_mul_f32 v[22:23], v[18:19], v[16:17]
	v_cvt_pk_bf16_f32 v16, v28, v29
	v_cvt_pk_bf16_f32 v17, v20, v21
	v_cvt_pk_bf16_f32 v18, v24, v25
	v_cvt_pk_bf16_f32 v19, v22, v23
	global_store_dwordx4 v[10:11], v[16:19], off
	v_lshl_add_u64 v[10:11], v[10:11], 0, s[10:11]
	s_nop 1
	s_waitcnt vmcnt(4) lgkmcnt(1)
	v_mov_b32_e32 v16, v96
	v_mov_b32_e32 v17, v97
	v_mov_b32_e32 v18, v98
	v_mov_b32_e32 v19, v99
	v_mov_b32_e32 v20, v64
	v_mov_b32_e32 v21, v65
	v_mov_b32_e32 v22, v66
	v_mov_b32_e32 v23, v67
	v_mov_b32_e32 v24, v80
	v_mov_b32_e32 v25, v81
	v_mov_b32_e32 v26, v82
	v_mov_b32_e32 v27, v83
	v_and_b32_e32 v31, 0xffff0000, v16
	v_lshlrev_b32_e32 v30, 16, v16
	v_and_b32_e32 v29, 0xffff0000, v20
	v_lshlrev_b32_e32 v28, 16, v20
	v_lshlrev_b32_e32 v20, 16, v17
	v_and_b32_e32 v33, 0xffff0000, v24
	v_lshlrev_b32_e32 v32, 16, v24
	v_pk_fma_f32 v[30:31], v[6:7], v[32:33], v[30:31]
	v_lshlrev_b32_e32 v16, 16, v25
	v_pk_mul_f32 v[28:29], v[30:31], v[28:29]
	v_and_b32_e32 v31, 0xffff0000, v21
	v_lshlrev_b32_e32 v30, 16, v21
	v_and_b32_e32 v21, 0xffff0000, v17
	v_and_b32_e32 v17, 0xffff0000, v25
	v_pk_fma_f32 v[16:17], v[8:9], v[16:17], v[20:21]
	v_and_b32_e32 v25, 0xffff0000, v18
	v_pk_mul_f32 v[20:21], v[16:17], v[30:31]
	v_lshlrev_b32_e32 v24, 16, v18
	v_and_b32_e32 v31, 0xffff0000, v26
	v_lshlrev_b32_e32 v30, 16, v26
	v_and_b32_e32 v17, 0xffff0000, v22
	v_lshlrev_b32_e32 v16, 16, v22
	v_pk_fma_f32 v[24:25], v[2:3], v[30:31], v[24:25]
	v_lshlrev_b32_e32 v22, 16, v19
	v_pk_mul_f32 v[24:25], v[24:25], v[16:17]
	v_and_b32_e32 v17, 0xffff0000, v23
	v_lshlrev_b32_e32 v16, 16, v23
	v_and_b32_e32 v23, 0xffff0000, v19
	v_and_b32_e32 v19, 0xffff0000, v27
	v_lshlrev_b32_e32 v18, 16, v27
	v_pk_fma_f32 v[18:19], v[4:5], v[18:19], v[22:23]
	s_nop 0
	v_pk_mul_f32 v[22:23], v[18:19], v[16:17]
	v_cvt_pk_bf16_f32 v16, v28, v29
	v_cvt_pk_bf16_f32 v17, v20, v21
	v_cvt_pk_bf16_f32 v18, v24, v25
	v_cvt_pk_bf16_f32 v19, v22, v23
	global_store_dwordx4 v[10:11], v[16:19], off
	v_lshl_add_u64 v[10:11], v[10:11], 0, s[10:11]
	s_nop 1
	s_waitcnt vmcnt(3) lgkmcnt(0)
	v_mov_b32_e32 v16, v100
	v_mov_b32_e32 v17, v101
	v_mov_b32_e32 v18, v102
	v_mov_b32_e32 v19, v103
	v_mov_b32_e32 v20, v68
	v_mov_b32_e32 v21, v69
	v_mov_b32_e32 v22, v70
	v_mov_b32_e32 v23, v71
	v_mov_b32_e32 v24, v84
	v_mov_b32_e32 v25, v85
	v_mov_b32_e32 v26, v86
	v_mov_b32_e32 v27, v87
	v_and_b32_e32 v31, 0xffff0000, v16
	v_lshlrev_b32_e32 v30, 16, v16
	v_and_b32_e32 v29, 0xffff0000, v20
	v_lshlrev_b32_e32 v28, 16, v20
	v_lshlrev_b32_e32 v20, 16, v17
	v_and_b32_e32 v33, 0xffff0000, v24
	v_lshlrev_b32_e32 v32, 16, v24
	v_pk_fma_f32 v[30:31], v[6:7], v[32:33], v[30:31]
	v_lshlrev_b32_e32 v16, 16, v25
	v_pk_mul_f32 v[28:29], v[30:31], v[28:29]
	v_and_b32_e32 v31, 0xffff0000, v21
	v_lshlrev_b32_e32 v30, 16, v21
	v_and_b32_e32 v21, 0xffff0000, v17
	v_and_b32_e32 v17, 0xffff0000, v25
	v_pk_fma_f32 v[16:17], v[8:9], v[16:17], v[20:21]
	v_and_b32_e32 v25, 0xffff0000, v18
	v_pk_mul_f32 v[20:21], v[16:17], v[30:31]
	v_lshlrev_b32_e32 v24, 16, v18
	v_and_b32_e32 v31, 0xffff0000, v26
	v_lshlrev_b32_e32 v30, 16, v26
	v_and_b32_e32 v17, 0xffff0000, v22
	v_lshlrev_b32_e32 v16, 16, v22
	v_pk_fma_f32 v[24:25], v[2:3], v[30:31], v[24:25]
	v_lshlrev_b32_e32 v22, 16, v19
	v_pk_mul_f32 v[24:25], v[24:25], v[16:17]
	v_and_b32_e32 v17, 0xffff0000, v23
	v_lshlrev_b32_e32 v16, 16, v23
	v_and_b32_e32 v23, 0xffff0000, v19
	v_and_b32_e32 v19, 0xffff0000, v27
	v_lshlrev_b32_e32 v18, 16, v27
	v_pk_fma_f32 v[18:19], v[4:5], v[18:19], v[22:23]
	s_nop 0
	v_pk_mul_f32 v[22:23], v[18:19], v[16:17]
	v_cvt_pk_bf16_f32 v16, v28, v29
	v_cvt_pk_bf16_f32 v17, v20, v21
	v_cvt_pk_bf16_f32 v18, v24, v25
	v_cvt_pk_bf16_f32 v19, v22, v23
	global_store_dwordx4 v[10:11], v[16:19], off
	v_lshl_add_u64 v[10:11], v[10:11], 0, s[10:11]
	s_nop 1
	s_branch .LBB0_497
